# speedup vs baseline: 1.0157x; 1.0007x over previous
.LBB0_897:
	s_and_b32 s28, s26, 0x10000
	s_xor_b32 s29, s28, 0x10000
	s_add_u32 m0, s29, s57
	s_add_u32 m0, m0, 0x1000
	v_or_b32_e32 v0, s28, v180
	v_add_u32_e32 v218, v0, v184
	v_add_u32_e32 v0, v0, v183
	s_waitcnt lgkmcnt(2)
	v_mfma_f32_16x16x32_bf16 v[158:161], v[2:5], v[202:205], v[158:161]
	global_load_lds_dwordx4 v166, s[60:61]
	s_add_u32 m0, m0, 0x400
	v_add_u32_e32 v218, v218, v181
	s_add_i32 s27, s27, -1
	v_mfma_f32_16x16x32_bf16 v[154:157], v[6:9], v[202:205], v[154:157]
	s_add_i32 s26, s26, 0x10000
	v_mfma_f32_16x16x32_bf16 v[150:153], v[10:13], v[202:205], v[150:153]
	global_load_lds_dwordx4 v167, s[60:61]
	s_add_u32 m0, m0, 0x400
	v_mfma_f32_16x16x32_bf16 v[146:149], v[14:17], v[202:205], v[146:149]
	ds_read_b128 v[202:205], v0 offset:6144
	s_waitcnt lgkmcnt(2)
	v_mfma_f32_16x16x32_bf16 v[142:145], v[2:5], v[206:209], v[142:145]
	global_load_lds_dwordx4 v168, s[60:61]
	s_add_u32 m0, m0, 0x400
	v_mfma_f32_16x16x32_bf16 v[138:141], v[6:9], v[206:209], v[138:141]
	v_mfma_f32_16x16x32_bf16 v[134:137], v[10:13], v[206:209], v[134:137]
	global_load_lds_dwordx4 v169, s[60:61]
	s_add_u32 s60, s60, 0x80
	s_addc_u32 s61, s61, 0
	v_mfma_f32_16x16x32_bf16 v[130:133], v[14:17], v[206:209], v[130:133]
	ds_read_b128 v[206:209], v0 offset:8192
	s_waitcnt lgkmcnt(2)
	v_mfma_f32_16x16x32_bf16 v[126:129], v[2:5], v[226:229], v[126:129]
	v_mfma_f32_16x16x32_bf16 v[122:125], v[6:9], v[226:229], v[122:125]
	v_mfma_f32_16x16x32_bf16 v[118:121], v[10:13], v[226:229], v[118:121]
	v_mfma_f32_16x16x32_bf16 v[114:117], v[14:17], v[226:229], v[114:117]
	ds_read_b128 v[226:229], v0 offset:10240
	s_waitcnt lgkmcnt(2)
	v_mfma_f32_16x16x32_bf16 v[106:109], v[2:5], v[202:205], v[106:109]
	v_mfma_f32_16x16x32_bf16 v[102:105], v[6:9], v[202:205], v[102:105]
	v_mfma_f32_16x16x32_bf16 v[98:101], v[10:13], v[202:205], v[98:101]
	v_mfma_f32_16x16x32_bf16 v[94:97], v[14:17], v[202:205], v[94:97]
	ds_read_b128 v[202:205], v0 offset:12288
	ds_read_b128 v[230:233], v218 offset:32768
	s_waitcnt lgkmcnt(3)
	v_mfma_f32_16x16x32_bf16 v[86:89], v[2:5], v[206:209], v[86:89]
	v_mfma_f32_16x16x32_bf16 v[82:85], v[6:9], v[206:209], v[82:85]
	v_mfma_f32_16x16x32_bf16 v[78:81], v[10:13], v[206:209], v[78:81]
	v_mfma_f32_16x16x32_bf16 v[74:77], v[14:17], v[206:209], v[74:77]
	ds_read_b128 v[206:209], v0 offset:14336
	ds_read_b128 v[234:237], v218 offset:34816
	v_add_u32_e32 v0, v0, v181
	s_waitcnt lgkmcnt(4)
	v_mfma_f32_16x16x32_bf16 v[70:73], v[2:5], v[226:229], v[70:73]
	v_mfma_f32_16x16x32_bf16 v[66:69], v[6:9], v[226:229], v[66:69]
	v_mfma_f32_16x16x32_bf16 v[62:65], v[10:13], v[226:229], v[62:65]
	v_mfma_f32_16x16x32_bf16 v[58:61], v[14:17], v[226:229], v[58:61]
	ds_read_b128 v[226:229], v0 offset:0
	ds_read_b128 v[238:241], v218 offset:36864
	s_waitcnt lgkmcnt(5)
	v_mfma_f32_16x16x32_bf16 v[54:57], v[2:5], v[202:205], v[54:57]
	v_mfma_f32_16x16x32_bf16 v[50:53], v[6:9], v[202:205], v[50:53]
	v_mfma_f32_16x16x32_bf16 v[46:49], v[10:13], v[202:205], v[46:49]
	v_mfma_f32_16x16x32_bf16 v[42:45], v[14:17], v[202:205], v[42:45]
	ds_read_b128 v[202:205], v0 offset:2048
	ds_read_b128 v[242:245], v218 offset:38912
	s_waitcnt lgkmcnt(5)
	v_mfma_f32_16x16x32_bf16 v[38:41], v[2:5], v[206:209], v[38:41]
	v_mfma_f32_16x16x32_bf16 v[34:37], v[6:9], v[206:209], v[34:37]
	v_mfma_f32_16x16x32_bf16 v[90:93], v[10:13], v[206:209], v[90:93]
	v_mfma_f32_16x16x32_bf16 v[110:113], v[14:17], v[206:209], v[110:113]
	ds_read_b128 v[186:189], v0 offset:4096
	s_waitcnt lgkmcnt(4)
	v_mfma_f32_16x16x32_bf16 v[158:161], v[230:233], v[226:229], v[158:161]
	v_mfma_f32_16x16x32_bf16 v[154:157], v[234:237], v[226:229], v[154:157]
	s_waitcnt lgkmcnt(3)
	v_mfma_f32_16x16x32_bf16 v[150:153], v[238:241], v[226:229], v[150:153]
	s_waitcnt lgkmcnt(1)
	v_mfma_f32_16x16x32_bf16 v[146:149], v[242:245], v[226:229], v[146:149]
	ds_read_b128 v[190:193], v0 offset:6144
	v_mfma_f32_16x16x32_bf16 v[142:145], v[230:233], v[202:205], v[142:145]
	v_mfma_f32_16x16x32_bf16 v[138:141], v[234:237], v[202:205], v[138:141]
	v_mfma_f32_16x16x32_bf16 v[134:137], v[238:241], v[202:205], v[134:137]
	v_mfma_f32_16x16x32_bf16 v[130:133], v[242:245], v[202:205], v[130:133]
	ds_read_b128 v[194:197], v0 offset:8192
	s_waitcnt lgkmcnt(2)
	v_mfma_f32_16x16x32_bf16 v[126:129], v[230:233], v[186:189], v[126:129]
	v_mfma_f32_16x16x32_bf16 v[122:125], v[234:237], v[186:189], v[122:125]
	v_mfma_f32_16x16x32_bf16 v[118:121], v[238:241], v[186:189], v[118:121]
	v_mfma_f32_16x16x32_bf16 v[114:117], v[242:245], v[186:189], v[114:117]
	ds_read_b128 v[186:189], v0 offset:10240
	s_waitcnt lgkmcnt(2)
	v_mfma_f32_16x16x32_bf16 v[106:109], v[230:233], v[190:193], v[106:109]
	v_mfma_f32_16x16x32_bf16 v[102:105], v[234:237], v[190:193], v[102:105]
	v_mfma_f32_16x16x32_bf16 v[98:101], v[238:241], v[190:193], v[98:101]
	v_mfma_f32_16x16x32_bf16 v[94:97], v[242:245], v[190:193], v[94:97]
	ds_read_b128 v[190:193], v0 offset:12288
	s_waitcnt lgkmcnt(2)
	v_mfma_f32_16x16x32_bf16 v[86:89], v[230:233], v[194:197], v[86:89]
	v_mfma_f32_16x16x32_bf16 v[82:85], v[234:237], v[194:197], v[82:85]
	v_mfma_f32_16x16x32_bf16 v[78:81], v[238:241], v[194:197], v[78:81]
	v_mfma_f32_16x16x32_bf16 v[74:77], v[242:245], v[194:197], v[74:77]
	ds_read_b128 v[194:197], v0 offset:14336
	s_waitcnt lgkmcnt(2)
	v_mfma_f32_16x16x32_bf16 v[70:73], v[230:233], v[186:189], v[70:73]
	v_mfma_f32_16x16x32_bf16 v[66:69], v[234:237], v[186:189], v[66:69]
	v_mfma_f32_16x16x32_bf16 v[62:65], v[238:241], v[186:189], v[62:65]
	v_mfma_f32_16x16x32_bf16 v[58:61], v[242:245], v[186:189], v[58:61]
	s_waitcnt vmcnt(0) lgkmcnt(0)
	s_barrier
; template <int NT, int BM, int BN, bool PLAIN, int NSTAGE, bool EPI_LDS>
; __device__ __forceinline__ void gemm_tile(const Params& p, const GemmDesc& g, bf16_t* lds, const int tid) {
;     ...
;     if (PLAIN) {
;       int kt = 0;
;       for (; kt + 2 < nk; ++kt) {
;         const int cur = kt & 1;
;         COMPUTE_X(cur, 1, 1, kt + 2)
;         __syncthreads();
;       }
;       if (kt + 1 < nk) {
;         const int cur = kt & 1;
;         COMPUTE_X(cur, 1, 0, 0)
;         __syncthreads();
;         ++kt;
;       }
;       {
;         const int cur = kt & 1;
;         COMPUTE_X(cur, 0, 0, 0)
;         __syncthreads();
	s_xor_b32 s29, s28, 0x10000
	v_or_b32_e32 v18, s29, v180
	v_add_u32_e32 v19, v18, v184
	v_add_u32_e32 v18, v18, v183
	ds_read_b128 v[2:5], v19 offset:32768
	ds_read_b128 v[6:9], v19 offset:34816
	ds_read_b128 v[10:13], v19 offset:36864
	ds_read_b128 v[14:17], v19 offset:38912
	ds_read_b128 v[202:205], v18
	ds_read_b128 v[206:209], v18 offset:2048
	ds_read_b128 v[226:229], v18 offset:4096
	s_add_u32 m0, s28, s57
	v_mfma_f32_16x16x32_bf16 v[54:57], v[230:233], v[190:193], v[54:57]
	global_load_lds_dwordx4 v162, s[60:61]
	s_add_u32 m0, m0, 0x400
	v_mfma_f32_16x16x32_bf16 v[50:53], v[234:237], v[190:193], v[50:53]
	v_mfma_f32_16x16x32_bf16 v[46:49], v[238:241], v[190:193], v[46:49]
	global_load_lds_dwordx4 v163, s[60:61]
	s_add_u32 m0, m0, 0x400
	v_mfma_f32_16x16x32_bf16 v[42:45], v[242:245], v[190:193], v[42:45]
	v_mfma_f32_16x16x32_bf16 v[38:41], v[230:233], v[194:197], v[38:41]
	global_load_lds_dwordx4 v164, s[60:61]
	s_add_u32 m0, m0, 0x400
	v_mfma_f32_16x16x32_bf16 v[34:37], v[234:237], v[194:197], v[34:37]
	v_mfma_f32_16x16x32_bf16 v[90:93], v[238:241], v[194:197], v[90:93]
	global_load_lds_dwordx4 v165, s[60:61]
	v_mfma_f32_16x16x32_bf16 v[110:113], v[242:245], v[194:197], v[110:113]
	s_cmp_lg_u32 s27, 0
	s_cbranch_scc1 .LBB0_897
	s_lshl_b32 s3, s3, 16
	s_and_b32 s3, s3, 0x10000
	s_xor_b32 s29, s3, 0x10000
	s_add_u32 m0, s29, s57
	s_add_u32 m0, m0, 0x1000
	s_nop 0
	global_load_lds_dwordx4 v166, s[60:61]
	s_add_u32 m0, m0, 0x400
	s_nop 0
	global_load_lds_dwordx4 v167, s[60:61]
	s_add_u32 m0, m0, 0x400
	s_nop 0
	global_load_lds_dwordx4 v168, s[60:61]
	s_add_u32 m0, m0, 0x400
	s_nop 0
	global_load_lds_dwordx4 v169, s[60:61]
	v_or_b32_e32 v0, s3, v180
	v_add_u32_e32 v198, v0, v184
	ds_read_b128 v[162:165], v198 offset:32768
	ds_read_b128 v[166:169], v198 offset:34816
	ds_read_b128 v[170:173], v198 offset:36864
	ds_read_b128 v[186:189], v198 offset:38912
	v_add_u32_e32 v0, v0, v183
	ds_read_b128 v[174:177], v0
	ds_read_b128 v[190:193], v0 offset:2048
	ds_read_b128 v[194:197], v0 offset:4096
	s_waitcnt lgkmcnt(2)
	v_mfma_f32_16x16x32_bf16 v[30:33], v[162:165], v[174:177], v[158:161]
	s_not_b32 s3, s23
	s_lshl_b32 s3, s3, 16
	s_and_b32 s3, s3, 0x10000
	v_mfma_f32_16x16x32_bf16 v[154:157], v[166:169], v[174:177], v[154:157]
	s_cmp_lg_u32 s56, 9
	s_cselect_b64 s[26:27], -1, 0
	s_mov_b32 s24, s41
	v_mfma_f32_16x16x32_bf16 v[150:153], v[170:173], v[174:177], v[150:153]
	s_mov_b32 s23, s42
	s_mov_b64 s[28:29], -1
	s_and_b64 vcc, exec, s[26:27]
	v_mfma_f32_16x16x32_bf16 v[146:149], v[186:189], v[174:177], v[146:149]
	ds_read_b128 v[158:161], v0 offset:6144
	v_add_u32_e32 v174, v198, v181
	s_waitcnt lgkmcnt(2)
	v_mfma_f32_16x16x32_bf16 v[26:29], v[162:165], v[190:193], v[142:145]
	v_mfma_f32_16x16x32_bf16 v[138:141], v[166:169], v[190:193], v[138:141]
	v_mfma_f32_16x16x32_bf16 v[134:137], v[170:173], v[190:193], v[134:137]
	v_mfma_f32_16x16x32_bf16 v[130:133], v[186:189], v[190:193], v[130:133]
	ds_read_b128 v[142:145], v0 offset:8192
	s_waitcnt lgkmcnt(2)
	v_mfma_f32_16x16x32_bf16 v[22:25], v[162:165], v[194:197], v[126:129]
	v_mfma_f32_16x16x32_bf16 v[122:125], v[166:169], v[194:197], v[122:125]
	v_mfma_f32_16x16x32_bf16 v[118:121], v[170:173], v[194:197], v[118:121]
	v_mfma_f32_16x16x32_bf16 v[114:117], v[186:189], v[194:197], v[114:117]
	ds_read_b128 v[126:129], v0 offset:10240
	s_waitcnt lgkmcnt(2)
	v_mfma_f32_16x16x32_bf16 v[18:21], v[162:165], v[158:161], v[106:109]
	v_mfma_f32_16x16x32_bf16 v[102:105], v[166:169], v[158:161], v[102:105]
	v_mfma_f32_16x16x32_bf16 v[98:101], v[170:173], v[158:161], v[98:101]
	v_mfma_f32_16x16x32_bf16 v[94:97], v[186:189], v[158:161], v[94:97]
	ds_read_b128 v[106:109], v0 offset:12288
	ds_read_b128 v[158:161], v174 offset:32768
	s_waitcnt lgkmcnt(3)
	v_mfma_f32_16x16x32_bf16 v[14:17], v[162:165], v[142:145], v[86:89]
	v_mfma_f32_16x16x32_bf16 v[82:85], v[166:169], v[142:145], v[82:85]
	v_mfma_f32_16x16x32_bf16 v[78:81], v[170:173], v[142:145], v[78:81]
	v_mfma_f32_16x16x32_bf16 v[74:77], v[186:189], v[142:145], v[74:77]
	ds_read_b128 v[86:89], v0 offset:14336
	ds_read_b128 v[142:145], v174 offset:34816
	v_add_u32_e32 v0, v0, v181
	s_waitcnt lgkmcnt(4)
	v_mfma_f32_16x16x32_bf16 v[10:13], v[162:165], v[126:129], v[70:73]
	v_mfma_f32_16x16x32_bf16 v[66:69], v[166:169], v[126:129], v[66:69]
	v_mfma_f32_16x16x32_bf16 v[62:65], v[170:173], v[126:129], v[62:65]
	v_mfma_f32_16x16x32_bf16 v[58:61], v[186:189], v[126:129], v[58:61]
	ds_read_b128 v[70:73], v0 offset:0
	ds_read_b128 v[126:129], v174 offset:36864
	s_waitcnt lgkmcnt(5)
	v_mfma_f32_16x16x32_bf16 v[6:9], v[162:165], v[106:109], v[54:57]
	v_mfma_f32_16x16x32_bf16 v[50:53], v[166:169], v[106:109], v[50:53]
	v_mfma_f32_16x16x32_bf16 v[46:49], v[170:173], v[106:109], v[46:49]
	v_mfma_f32_16x16x32_bf16 v[42:45], v[186:189], v[106:109], v[42:45]
	ds_read_b128 v[106:109], v174 offset:38912
	ds_read_b128 v[54:57], v0 offset:2048
	s_waitcnt lgkmcnt(5)
	v_mfma_f32_16x16x32_bf16 v[2:5], v[162:165], v[86:89], v[38:41]
	v_mfma_f32_16x16x32_bf16 v[34:37], v[166:169], v[86:89], v[34:37]
	v_mfma_f32_16x16x32_bf16 v[38:41], v[170:173], v[86:89], v[90:93]
	v_mfma_f32_16x16x32_bf16 v[86:89], v[186:189], v[86:89], v[110:113]
	s_nop 1
	ds_read_b128 v[90:93], v0 offset:4096
	s_waitcnt lgkmcnt(4)
	v_mfma_f32_16x16x32_bf16 v[30:33], v[158:161], v[70:73], v[30:33]
	v_mfma_f32_16x16x32_bf16 v[110:113], v[142:145], v[70:73], v[154:157]
	s_waitcnt lgkmcnt(3)
	v_mfma_f32_16x16x32_bf16 v[150:153], v[126:129], v[70:73], v[150:153]
	s_waitcnt lgkmcnt(2)
	v_mfma_f32_16x16x32_bf16 v[70:73], v[106:109], v[70:73], v[146:149]
	s_nop 2
	ds_read_b128 v[146:149], v0 offset:6144
	s_waitcnt lgkmcnt(2)
	v_mfma_f32_16x16x32_bf16 v[26:29], v[158:161], v[54:57], v[26:29]
	v_mfma_f32_16x16x32_bf16 v[138:141], v[142:145], v[54:57], v[138:141]
	v_mfma_f32_16x16x32_bf16 v[134:137], v[126:129], v[54:57], v[134:137]
	v_mfma_f32_16x16x32_bf16 v[54:57], v[106:109], v[54:57], v[130:133]
	s_nop 2
	ds_read_b128 v[130:133], v0 offset:8192
	s_waitcnt lgkmcnt(2)
	v_mfma_f32_16x16x32_bf16 v[22:25], v[158:161], v[90:93], v[22:25]
	v_mfma_f32_16x16x32_bf16 v[122:125], v[142:145], v[90:93], v[122:125]
	v_mfma_f32_16x16x32_bf16 v[118:121], v[126:129], v[90:93], v[118:121]
	v_mfma_f32_16x16x32_bf16 v[90:93], v[106:109], v[90:93], v[114:117]
	s_nop 2
	ds_read_b128 v[114:117], v0 offset:10240
	s_waitcnt lgkmcnt(2)
	v_mfma_f32_16x16x32_bf16 v[18:21], v[158:161], v[146:149], v[18:21]
	v_mfma_f32_16x16x32_bf16 v[102:105], v[142:145], v[146:149], v[102:105]
	v_mfma_f32_16x16x32_bf16 v[98:101], v[126:129], v[146:149], v[98:101]
	v_mfma_f32_16x16x32_bf16 v[94:97], v[106:109], v[146:149], v[94:97]
	ds_read_b128 v[146:149], v0 offset:12288
	s_waitcnt lgkmcnt(2)
	v_mfma_f32_16x16x32_bf16 v[14:17], v[158:161], v[130:133], v[14:17]
	v_mfma_f32_16x16x32_bf16 v[82:85], v[142:145], v[130:133], v[82:85]
	v_mfma_f32_16x16x32_bf16 v[78:81], v[126:129], v[130:133], v[78:81]
	v_mfma_f32_16x16x32_bf16 v[74:77], v[106:109], v[130:133], v[74:77]
	ds_read_b128 v[130:133], v0 offset:14336
	v_or_b32_e32 v0, s3, v180
	v_add_u32_e32 v186, v0, v184
	s_waitcnt lgkmcnt(2)
	v_mfma_f32_16x16x32_bf16 v[10:13], v[158:161], v[114:117], v[10:13]
	s_waitcnt vmcnt(0) lgkmcnt(0)
	s_barrier
; template <int NT, int BM, int BN, bool PLAIN, int NSTAGE, bool EPI_LDS>
; __device__ __forceinline__ void gemm_tile(const Params& p, const GemmDesc& g, bf16_t* lds, const int tid) {
;     ...
;   if (EPI_LDS) {
;     constexpr int CST = BN + 16;
;     bf16_t* ct = lds;
;     const bool relu2 = (g.epi == E_RELU2);
; #pragma unroll
;     for (int mi = 0; mi < MI; ++mi)
; #pragma unroll
;       for (int ni = 0; ni < NI; ++ni) {
;         f32x4 v = acc[mi][ni];
;         if (relu2) {
; #pragma unroll
;           for (int j = 0; j < 4; ++j) { const float r = fmaxf(v[j], 0.f); v[j] = r * r; }
;         }
;         u32x2 w;
;         w[0] = pack2(v[0], v[1]);
;         w[1] = pack2(v[2], v[3]);
;         *(u32x2*)(ct + (wm * WTM + mi * 16 + fr) * CST + wn * WTN + ni * 16 + fq * 4) = w;
;       }
	v_mfma_f32_16x16x32_bf16 v[66:69], v[142:145], v[114:117], v[66:69]
	v_add_u32_e32 v0, v0, v183
	v_mfma_f32_16x16x32_bf16 v[62:65], v[126:129], v[114:117], v[62:65]
	v_mfma_f32_16x16x32_bf16 v[58:61], v[106:109], v[114:117], v[58:61]
	v_mfma_f32_16x16x32_bf16 v[6:9], v[158:161], v[146:149], v[6:9]
	v_mfma_f32_16x16x32_bf16 v[50:53], v[142:145], v[146:149], v[50:53]
	v_mfma_f32_16x16x32_bf16 v[46:49], v[126:129], v[146:149], v[46:49]
	v_mfma_f32_16x16x32_bf16 v[42:45], v[106:109], v[146:149], v[42:45]
	v_mfma_f32_16x16x32_bf16 v[2:5], v[158:161], v[130:133], v[2:5]
	v_mfma_f32_16x16x32_bf16 v[34:37], v[142:145], v[130:133], v[34:37]
	v_mfma_f32_16x16x32_bf16 v[38:41], v[126:129], v[130:133], v[38:41]
	v_mfma_f32_16x16x32_bf16 v[86:89], v[106:109], v[130:133], v[86:89]
	ds_read_b128 v[106:109], v186 offset:32768
	ds_read_b128 v[114:117], v186 offset:34816
	ds_read_b128 v[130:133], v186 offset:36864
	ds_read_b128 v[142:145], v186 offset:38912
	ds_read_b128 v[126:129], v0
	ds_read_b128 v[146:149], v0 offset:2048
	ds_read_b128 v[154:157], v0 offset:4096
	s_waitcnt lgkmcnt(2)
	v_mfma_f32_16x16x32_bf16 v[30:33], v[106:109], v[126:129], v[30:33]
	v_mfma_f32_16x16x32_bf16 v[110:113], v[114:117], v[126:129], v[110:113]
	v_mfma_f32_16x16x32_bf16 v[150:153], v[130:133], v[126:129], v[150:153]
	v_mfma_f32_16x16x32_bf16 v[70:73], v[142:145], v[126:129], v[70:73]
	ds_read_b128 v[126:129], v0 offset:6144
	s_waitcnt lgkmcnt(2)
	v_mfma_f32_16x16x32_bf16 v[26:29], v[106:109], v[146:149], v[26:29]
	v_mfma_f32_16x16x32_bf16 v[138:141], v[114:117], v[146:149], v[138:141]
	v_mfma_f32_16x16x32_bf16 v[134:137], v[130:133], v[146:149], v[134:137]
	v_mfma_f32_16x16x32_bf16 v[54:57], v[142:145], v[146:149], v[54:57]
	ds_read_b128 v[146:149], v0 offset:8192
	s_waitcnt lgkmcnt(2)
	v_mfma_f32_16x16x32_bf16 v[22:25], v[106:109], v[154:157], v[22:25]
	v_mfma_f32_16x16x32_bf16 v[158:161], v[114:117], v[154:157], v[122:125]
	v_mfma_f32_16x16x32_bf16 v[162:165], v[130:133], v[154:157], v[118:121]
	v_mfma_f32_16x16x32_bf16 v[154:157], v[142:145], v[154:157], v[90:93]
	s_nop 2
	ds_read_b128 v[90:93], v0 offset:10240
	s_waitcnt lgkmcnt(2)
	v_mfma_f32_16x16x32_bf16 v[18:21], v[106:109], v[126:129], v[18:21]
	v_mfma_f32_16x16x32_bf16 v[166:169], v[114:117], v[126:129], v[102:105]
	v_mfma_f32_16x16x32_bf16 v[170:173], v[130:133], v[126:129], v[98:101]
	v_mfma_f32_16x16x32_bf16 v[174:177], v[142:145], v[126:129], v[94:97]
	s_nop 1
	v_add_u32_e32 v98, v186, v181
	ds_read_b128 v[186:189], v98 offset:32768
	ds_read_b128 v[94:97], v0 offset:12288
	s_waitcnt lgkmcnt(3)
	v_mfma_f32_16x16x32_bf16 v[14:17], v[106:109], v[146:149], v[14:17]
	v_mfma_f32_16x16x32_bf16 v[190:193], v[114:117], v[146:149], v[82:85]
	v_mfma_f32_16x16x32_bf16 v[194:197], v[130:133], v[146:149], v[78:81]
	v_mfma_f32_16x16x32_bf16 v[146:149], v[142:145], v[146:149], v[74:77]
	ds_read_b128 v[198:201], v98 offset:34816
	s_nop 1
	ds_read_b128 v[74:77], v0 offset:14336
	v_add_u32_e32 v0, v0, v181
	s_waitcnt lgkmcnt(4)
	v_mfma_f32_16x16x32_bf16 v[10:13], v[106:109], v[90:93], v[10:13]
	v_mfma_f32_16x16x32_bf16 v[202:205], v[114:117], v[90:93], v[66:69]
	v_mfma_f32_16x16x32_bf16 v[206:209], v[130:133], v[90:93], v[62:65]
	v_mfma_f32_16x16x32_bf16 v[226:229], v[142:145], v[90:93], v[58:61]
	ds_read_b128 v[230:233], v98 offset:36864
	s_nop 1
	ds_read_b128 v[58:61], v0 offset:0
	s_waitcnt lgkmcnt(4)
	v_mfma_f32_16x16x32_bf16 v[6:9], v[106:109], v[94:97], v[6:9]
	v_mfma_f32_16x16x32_bf16 v[234:237], v[114:117], v[94:97], v[50:53]
	v_mfma_f32_16x16x32_bf16 v[238:241], v[130:133], v[94:97], v[46:49]
	v_mfma_f32_16x16x32_bf16 v[242:245], v[142:145], v[94:97], v[42:45]
	ds_read_b128 v[246:249], v98 offset:38912
	s_nop 1
	ds_read_b128 v[42:45], v0 offset:2048
	s_waitcnt lgkmcnt(4)
	v_mfma_f32_16x16x32_bf16 v[2:5], v[106:109], v[74:77], v[2:5]
	v_mfma_f32_16x16x32_bf16 v[218:221], v[114:117], v[74:77], v[34:37]
	v_mfma_f32_16x16x32_bf16 v[130:133], v[130:133], v[74:77], v[38:41]
	v_mfma_f32_16x16x32_bf16 v[142:145], v[142:145], v[74:77], v[86:89]
	s_nop 0
	ds_read_b128 v[34:37], v0 offset:4096
	s_waitcnt lgkmcnt(3)
	v_mfma_f32_16x16x32_bf16 v[126:129], v[186:189], v[58:61], v[30:33]
	v_mfma_f32_16x16x32_bf16 v[122:125], v[198:201], v[58:61], v[110:113]
	v_mfma_f32_16x16x32_bf16 v[118:121], v[230:233], v[58:61], v[150:153]
	s_waitcnt lgkmcnt(2)
	v_mfma_f32_16x16x32_bf16 v[114:117], v[246:249], v[58:61], v[70:73]
	ds_read_b128 v[30:33], v0 offset:6144
	s_waitcnt lgkmcnt(2)
	v_mfma_f32_16x16x32_bf16 v[110:113], v[186:189], v[42:45], v[26:29]
	v_mfma_f32_16x16x32_bf16 v[106:109], v[198:201], v[42:45], v[138:141]
	v_mfma_f32_16x16x32_bf16 v[102:105], v[230:233], v[42:45], v[134:137]
	v_mfma_f32_16x16x32_bf16 v[98:101], v[246:249], v[42:45], v[54:57]
	ds_read_b128 v[26:29], v0 offset:8192
	s_waitcnt lgkmcnt(2)
	v_mfma_f32_16x16x32_bf16 v[94:97], v[186:189], v[34:37], v[22:25]
	v_mfma_f32_16x16x32_bf16 v[90:93], v[198:201], v[34:37], v[158:161]
	v_mfma_f32_16x16x32_bf16 v[86:89], v[230:233], v[34:37], v[162:165]
	v_mfma_f32_16x16x32_bf16 v[82:85], v[246:249], v[34:37], v[154:157]
	ds_read_b128 v[22:25], v0 offset:10240
	s_waitcnt lgkmcnt(2)
	v_mfma_f32_16x16x32_bf16 v[78:81], v[186:189], v[30:33], v[18:21]
	v_mfma_f32_16x16x32_bf16 v[74:77], v[198:201], v[30:33], v[166:169]
	v_mfma_f32_16x16x32_bf16 v[70:73], v[230:233], v[30:33], v[170:173]
	v_mfma_f32_16x16x32_bf16 v[66:69], v[246:249], v[30:33], v[174:177]
	ds_read_b128 v[18:21], v0 offset:12288
	s_waitcnt lgkmcnt(2)
	v_mfma_f32_16x16x32_bf16 v[62:65], v[186:189], v[26:29], v[14:17]
	v_mfma_f32_16x16x32_bf16 v[58:61], v[198:201], v[26:29], v[190:193]
	v_mfma_f32_16x16x32_bf16 v[54:57], v[230:233], v[26:29], v[194:197]
	v_mfma_f32_16x16x32_bf16 v[50:53], v[246:249], v[26:29], v[146:149]
	ds_read_b128 v[134:137], v0 offset:14336
	s_waitcnt lgkmcnt(0)
	s_barrier
	v_mfma_f32_16x16x32_bf16 v[46:49], v[186:189], v[22:25], v[10:13]
	v_mfma_f32_16x16x32_bf16 v[42:45], v[198:201], v[22:25], v[202:205]
	v_mfma_f32_16x16x32_bf16 v[38:41], v[230:233], v[22:25], v[206:209]
	v_mfma_f32_16x16x32_bf16 v[34:37], v[246:249], v[22:25], v[226:229]
	v_mfma_f32_16x16x32_bf16 v[30:33], v[186:189], v[18:21], v[6:9]
	v_mfma_f32_16x16x32_bf16 v[26:29], v[198:201], v[18:21], v[234:237]
	v_mfma_f32_16x16x32_bf16 v[22:25], v[230:233], v[18:21], v[238:241]
	v_mfma_f32_16x16x32_bf16 v[18:21], v[246:249], v[18:21], v[242:245]
	v_mfma_f32_16x16x32_bf16 v[14:17], v[186:189], v[134:137], v[2:5]
	v_mfma_f32_16x16x32_bf16 v[10:13], v[198:201], v[134:137], v[218:221]
	v_mfma_f32_16x16x32_bf16 v[2:5], v[230:233], v[134:137], v[130:133]
	v_mfma_f32_16x16x32_bf16 v[6:9], v[246:249], v[134:137], v[142:145]
	s_cbranch_vccz .LBB0_900
	s_nop 0
	v_cvt_pk_bf16_f32 v130, v126, v127
	v_cvt_pk_bf16_f32 v131, v128, v129
	s_mov_b64 s[28:29], 0
